# v43 + s_nop pad between v_cmp vcc and v_cndmask in the rare softmax rescale path (hazard safety, no hot-path change)
# speedup vs baseline: 1.0024x; 1.0017x over previous
.LBB0_935:
	v_sub_f32_e32 v241, v164, v184
	v_max_f32_e32 v241, v160, v241
	v_sub_f32_e32 v163, v160, v241
	v_exp_f32_e32 v163, v163
	v_add_f32_e32 v242, v241, v184
	v_mov_b32_e32 v160, v241
	v_sub_f32_e32 v84, v84, v242
	v_sub_f32_e32 v85, v85, v242
	v_sub_f32_e32 v86, v86, v242
	v_sub_f32_e32 v87, v87, v242
	v_sub_f32_e32 v88, v88, v242
	v_sub_f32_e32 v89, v89, v242
	v_sub_f32_e32 v90, v90, v242
	v_sub_f32_e32 v91, v91, v242
	v_sub_f32_e32 v92, v92, v242
	v_sub_f32_e32 v93, v93, v242
	v_sub_f32_e32 v94, v94, v242
	v_sub_f32_e32 v95, v95, v242
	v_sub_f32_e32 v96, v96, v242
	v_sub_f32_e32 v97, v97, v242
	v_sub_f32_e32 v98, v98, v242
	v_sub_f32_e32 v99, v99, v242
	v_sub_f32_e32 v68, v68, v242
	v_sub_f32_e32 v69, v69, v242
	v_sub_f32_e32 v70, v70, v242
	v_sub_f32_e32 v71, v71, v242
	v_sub_f32_e32 v72, v72, v242
	v_sub_f32_e32 v73, v73, v242
	v_sub_f32_e32 v74, v74, v242
	v_sub_f32_e32 v75, v75, v242
	v_sub_f32_e32 v76, v76, v242
	v_sub_f32_e32 v77, v77, v242
	v_sub_f32_e32 v78, v78, v242
	v_sub_f32_e32 v79, v79, v242
	v_sub_f32_e32 v80, v80, v242
	v_sub_f32_e32 v81, v81, v242
	v_sub_f32_e32 v82, v82, v242
	v_sub_f32_e32 v83, v83, v242
	v_cmp_lt_f32_e32 vcc, 0xf0000000, v241
	v_sub_f32_e32 v242, 0, v241
	s_nop 0
	v_cndmask_b32_e32 v242, 0, v242, vcc
	v_add_f32_e32 v240, v241, v242
	v_mov_b32_e32 v184, v242
	v_mov_b32_e32 v185, v242
	v_mov_b32_e32 v186, v242
	v_mov_b32_e32 v187, v242
	v_mov_b32_e32 v188, v242
	v_mov_b32_e32 v189, v242
	v_mov_b32_e32 v190, v242
	v_mov_b32_e32 v191, v242
	v_mov_b32_e32 v192, v242
	v_mov_b32_e32 v193, v242
	v_mov_b32_e32 v194, v242
	v_mov_b32_e32 v195, v242
	v_mov_b32_e32 v196, v242
	v_mov_b32_e32 v197, v242
	v_mov_b32_e32 v198, v242
	v_mov_b32_e32 v199, v242
	s_branch .LBB0_924

.LBB0_961:
	v_sub_f32_e32 v241, v166, v184
	v_max_f32_e32 v241, v162, v241
	v_sub_f32_e32 v165, v162, v241
	v_exp_f32_e32 v165, v165
	v_add_f32_e32 v242, v241, v184
	v_mov_b32_e32 v162, v241
	v_sub_f32_e32 v84, v84, v242
	v_sub_f32_e32 v85, v85, v242
	v_sub_f32_e32 v86, v86, v242
	v_sub_f32_e32 v87, v87, v242
	v_sub_f32_e32 v88, v88, v242
	v_sub_f32_e32 v89, v89, v242
	v_sub_f32_e32 v90, v90, v242
	v_sub_f32_e32 v91, v91, v242
	v_sub_f32_e32 v92, v92, v242
	v_sub_f32_e32 v93, v93, v242
	v_sub_f32_e32 v94, v94, v242
	v_sub_f32_e32 v95, v95, v242
	v_sub_f32_e32 v96, v96, v242
	v_sub_f32_e32 v97, v97, v242
	v_sub_f32_e32 v98, v98, v242
	v_sub_f32_e32 v99, v99, v242
	v_sub_f32_e32 v68, v68, v242
	v_sub_f32_e32 v69, v69, v242
	v_sub_f32_e32 v70, v70, v242
	v_sub_f32_e32 v71, v71, v242
	v_sub_f32_e32 v72, v72, v242
	v_sub_f32_e32 v73, v73, v242
	v_sub_f32_e32 v74, v74, v242
	v_sub_f32_e32 v75, v75, v242
	v_sub_f32_e32 v76, v76, v242
	v_sub_f32_e32 v77, v77, v242
	v_sub_f32_e32 v78, v78, v242
	v_sub_f32_e32 v79, v79, v242
	v_sub_f32_e32 v80, v80, v242
	v_sub_f32_e32 v81, v81, v242
	v_sub_f32_e32 v82, v82, v242
	v_sub_f32_e32 v83, v83, v242
	v_cmp_lt_f32_e32 vcc, 0xf0000000, v241
	v_sub_f32_e32 v242, 0, v241
	s_nop 0
	v_cndmask_b32_e32 v242, 0, v242, vcc
	v_add_f32_e32 v240, v241, v242
	v_mov_b32_e32 v184, v242
	v_mov_b32_e32 v185, v242
	v_mov_b32_e32 v186, v242
	v_mov_b32_e32 v187, v242
	v_mov_b32_e32 v188, v242
	v_mov_b32_e32 v189, v242
	v_mov_b32_e32 v190, v242
	v_mov_b32_e32 v191, v242
	v_mov_b32_e32 v192, v242
	v_mov_b32_e32 v193, v242
	v_mov_b32_e32 v194, v242
	v_mov_b32_e32 v195, v242
	v_mov_b32_e32 v196, v242
	v_mov_b32_e32 v197, v242
	v_mov_b32_e32 v198, v242
	v_mov_b32_e32 v199, v242
	s_branch .LBB0_950
